# E28: mem-attention prompt-unit epilogue (both layers) fast path: in-place scale+cvt, v_permlane32_swap pairing, 8 dwordx4 stores instead of 16 branchy dwordx2 (guide 7.3); on E27
# baseline (speedup 1.0000x reference)
.LBB0_339:
	ds_bpermute_b32 v4, v193, v165
	v_cmp_gt_i32_e32 vcc, s76, v170
	s_waitcnt lgkmcnt(0)
	s_barrier
	s_and_saveexec_b64 s[50:51], vcc
	s_cbranch_execz .LBB0_404
	v_add_f32_e32 v4, v165, v4
	v_div_scale_f32 v6, s[4:5], v4, v4, 1.0
	v_rcp_f32_e32 v7, v6
	s_add_i32 s4, s6, 0xffffc000
	s_bitset1_b32 s18, 9
	s_cmp_gt_i32 s4, -1
	v_fma_f32 v8, -v6, v7, 1.0
	v_fmac_f32_e32 v7, v8, v7
	v_div_scale_f32 v8, vcc, 1.0, v4, 1.0
	v_mul_f32_e32 v9, v8, v7
	v_fma_f32 v10, -v6, v9, v8
	v_fmac_f32_e32 v9, v10, v7
	v_fma_f32 v6, -v6, v9, v8
	v_div_fmas_f32 v6, v6, v7, v9
	v_div_fixup_f32 v8, v6, v4, 1.0
	v_add_u32_e32 v4, s4, v212
	v_add_u32_e32 v6, s47, v4
	v_ashrrev_i32_e32 v6, 5, v6
	v_ashrrev_i32_e32 v7, 31, v6
	v_pk_mul_f32 v[10:11], v[68:69], v[8:9] op_sel_hi:[1,0]
	s_cselect_b64 s[58:59], -1, 0
	s_and_b64 vcc, exec, s[58:59]
	s_cbranch_vccnz .Lmemw0_slow
	v_mov_b32_e32 v9, v8
	v_ashrrev_i32_e32 v171, 31, v170
	v_lshlrev_b64 v[10:11], 11, v[170:171]
	v_lshl_add_u64 v[10:11], v[158:159], 0, v[10:11]
	v_and_b32_e32 v12, 32, v217
	v_lshrrev_b32_e32 v12, 2, v12
	v_mov_b32_e32 v13, 0
	v_lshl_add_u64 v[10:11], v[10:11], 0, v[12:13]
	v_pk_mul_f32 v[68:69], v[68:69], v[8:9]
	v_pk_mul_f32 v[70:71], v[70:71], v[8:9]
	v_pk_mul_f32 v[72:73], v[72:73], v[8:9]
	v_pk_mul_f32 v[74:75], v[74:75], v[8:9]
	v_cvt_pk_bf16_f32 v68, v68, v69
	v_cvt_pk_bf16_f32 v69, v70, v71
	v_cvt_pk_bf16_f32 v70, v72, v73
	v_cvt_pk_bf16_f32 v71, v74, v75
	s_nop 1
	v_permlane32_swap_b32_e32 v68, v70
	v_permlane32_swap_b32_e32 v69, v71
	global_store_dwordx4 v[10:11], v[68:71], off
	v_pk_mul_f32 v[76:77], v[76:77], v[8:9]
	v_pk_mul_f32 v[78:79], v[78:79], v[8:9]
	v_pk_mul_f32 v[80:81], v[80:81], v[8:9]
	v_pk_mul_f32 v[82:83], v[82:83], v[8:9]
	v_cvt_pk_bf16_f32 v76, v76, v77
	v_cvt_pk_bf16_f32 v77, v78, v79
	v_cvt_pk_bf16_f32 v78, v80, v81
	v_cvt_pk_bf16_f32 v79, v82, v83
	s_nop 1
	v_permlane32_swap_b32_e32 v76, v78
	v_permlane32_swap_b32_e32 v77, v79
	global_store_dwordx4 v[10:11], v[76:79], off offset:32
	v_pk_mul_f32 v[52:53], v[52:53], v[8:9]
	v_pk_mul_f32 v[54:55], v[54:55], v[8:9]
	v_pk_mul_f32 v[56:57], v[56:57], v[8:9]
	v_pk_mul_f32 v[58:59], v[58:59], v[8:9]
	v_cvt_pk_bf16_f32 v52, v52, v53
	v_cvt_pk_bf16_f32 v53, v54, v55
	v_cvt_pk_bf16_f32 v54, v56, v57
	v_cvt_pk_bf16_f32 v55, v58, v59
	s_nop 1
	v_permlane32_swap_b32_e32 v52, v54
	v_permlane32_swap_b32_e32 v53, v55
	global_store_dwordx4 v[10:11], v[52:55], off offset:64
	v_pk_mul_f32 v[60:61], v[60:61], v[8:9]
	v_pk_mul_f32 v[62:63], v[62:63], v[8:9]
	v_pk_mul_f32 v[64:65], v[64:65], v[8:9]
	v_pk_mul_f32 v[66:67], v[66:67], v[8:9]
	v_cvt_pk_bf16_f32 v60, v60, v61
	v_cvt_pk_bf16_f32 v61, v62, v63
	v_cvt_pk_bf16_f32 v62, v64, v65
	v_cvt_pk_bf16_f32 v63, v66, v67
	s_nop 1
	v_permlane32_swap_b32_e32 v60, v62
	v_permlane32_swap_b32_e32 v61, v63
	global_store_dwordx4 v[10:11], v[60:63], off offset:96
	v_pk_mul_f32 v[36:37], v[36:37], v[8:9]
	v_pk_mul_f32 v[38:39], v[38:39], v[8:9]
	v_pk_mul_f32 v[40:41], v[40:41], v[8:9]
	v_pk_mul_f32 v[42:43], v[42:43], v[8:9]
	v_cvt_pk_bf16_f32 v36, v36, v37
	v_cvt_pk_bf16_f32 v37, v38, v39
	v_cvt_pk_bf16_f32 v38, v40, v41
	v_cvt_pk_bf16_f32 v39, v42, v43
	s_nop 1
	v_permlane32_swap_b32_e32 v36, v38
	v_permlane32_swap_b32_e32 v37, v39
	global_store_dwordx4 v[10:11], v[36:39], off offset:128
	v_pk_mul_f32 v[44:45], v[44:45], v[8:9]
	v_pk_mul_f32 v[46:47], v[46:47], v[8:9]
	v_pk_mul_f32 v[48:49], v[48:49], v[8:9]
	v_pk_mul_f32 v[50:51], v[50:51], v[8:9]
	v_cvt_pk_bf16_f32 v44, v44, v45
	v_cvt_pk_bf16_f32 v45, v46, v47
	v_cvt_pk_bf16_f32 v46, v48, v49
	v_cvt_pk_bf16_f32 v47, v50, v51
	s_nop 1
	v_permlane32_swap_b32_e32 v44, v46
	v_permlane32_swap_b32_e32 v45, v47
	global_store_dwordx4 v[10:11], v[44:47], off offset:160
	v_pk_mul_f32 v[20:21], v[20:21], v[8:9]
	v_pk_mul_f32 v[22:23], v[22:23], v[8:9]
	v_pk_mul_f32 v[24:25], v[24:25], v[8:9]
	v_pk_mul_f32 v[26:27], v[26:27], v[8:9]
	v_cvt_pk_bf16_f32 v20, v20, v21
	v_cvt_pk_bf16_f32 v21, v22, v23
	v_cvt_pk_bf16_f32 v22, v24, v25
	v_cvt_pk_bf16_f32 v23, v26, v27
	s_nop 1
	v_permlane32_swap_b32_e32 v20, v22
	v_permlane32_swap_b32_e32 v21, v23
	global_store_dwordx4 v[10:11], v[20:23], off offset:192
	v_pk_mul_f32 v[28:29], v[28:29], v[8:9]
	v_pk_mul_f32 v[30:31], v[30:31], v[8:9]
	v_pk_mul_f32 v[32:33], v[32:33], v[8:9]
	v_pk_mul_f32 v[34:35], v[34:35], v[8:9]
	v_cvt_pk_bf16_f32 v28, v28, v29
	v_cvt_pk_bf16_f32 v29, v30, v31
	v_cvt_pk_bf16_f32 v30, v32, v33
	v_cvt_pk_bf16_f32 v31, v34, v35
	s_nop 1
	v_permlane32_swap_b32_e32 v28, v30
	v_permlane32_swap_b32_e32 v29, v31
	global_store_dwordx4 v[10:11], v[28:31], off offset:224
	s_branch .LBB0_404
.Lmemw0_slow:
	v_lshlrev_b64 v[6:7], 12, v[6:7]
	v_cvt_pk_bf16_f32 v12, v10, v11
	v_pk_mul_f32 v[10:11], v[70:71], v[8:9] op_sel_hi:[1,0]
	v_and_b32_e32 v4, 31, v4
	v_cvt_pk_bf16_f32 v13, v10, v11
	s_mov_b64 s[4:5], -1
	s_and_b64 vcc, exec, s[58:59]
	v_lshl_or_b32 v14, s18, 2, v6
	s_cbranch_vccz .LBB0_342
	v_or_b32_e32 v10, v14, v4
	v_mov_b32_e32 v11, v7
	v_lshl_add_u64 v[10:11], v[10:11], 4, v[158:159]
	global_store_dwordx2 v[10:11], v[12:13], off
	s_mov_b64 s[4:5], 0

.LBB0_1251:
	ds_bpermute_b32 v2, v177, v153
	v_cmp_gt_i32_e32 vcc, s3, v156
	s_waitcnt lgkmcnt(0)
	s_barrier
	s_and_saveexec_b64 s[36:37], vcc
	s_cbranch_execz .LBB0_1316
	v_add_f32_e32 v2, v153, v2
	v_div_scale_f32 v4, s[8:9], v2, v2, 1.0
	v_rcp_f32_e32 v5, v4
	s_or_b32 s7, s60, 0x200
	v_cmp_gt_i64_e64 s[20:21], s[22:23], v[154:155]
	s_mov_b64 s[18:19], -1
	v_fma_f32 v6, -v4, v5, 1.0
	v_fmac_f32_e32 v5, v6, v5
	v_div_scale_f32 v6, vcc, 1.0, v2, 1.0
	v_mul_f32_e32 v7, v6, v5
	v_fma_f32 v8, -v4, v7, v6
	v_fmac_f32_e32 v7, v8, v5
	v_fma_f32 v4, -v4, v7, v6
	v_div_fmas_f32 v4, v4, v5, v7
	v_div_fixup_f32 v6, v4, v2, 1.0
	s_and_b64 vcc, exec, s[20:21]
	s_cbranch_vccnz .Lmemw1_slow
	v_mov_b32_e32 v7, v6
	v_ashrrev_i32_e32 v157, 31, v156
	v_lshlrev_b64 v[8:9], 11, v[156:157]
	v_lshl_add_u64 v[8:9], v[150:151], 0, v[8:9]
	v_and_b32_e32 v10, 32, v217
	v_lshrrev_b32_e32 v10, 2, v10
	v_mov_b32_e32 v11, 0
	v_lshl_add_u64 v[8:9], v[8:9], 0, v[10:11]
	v_pk_mul_f32 v[66:67], v[66:67], v[6:7]
	v_pk_mul_f32 v[68:69], v[68:69], v[6:7]
	v_pk_mul_f32 v[70:71], v[70:71], v[6:7]
	v_pk_mul_f32 v[72:73], v[72:73], v[6:7]
	v_cvt_pk_bf16_f32 v66, v66, v67
	v_cvt_pk_bf16_f32 v67, v68, v69
	v_cvt_pk_bf16_f32 v68, v70, v71
	v_cvt_pk_bf16_f32 v69, v72, v73
	s_nop 1
	v_permlane32_swap_b32_e32 v66, v68
	v_permlane32_swap_b32_e32 v67, v69
	global_store_dwordx4 v[8:9], v[66:69], off
	v_pk_mul_f32 v[74:75], v[74:75], v[6:7]
	v_pk_mul_f32 v[76:77], v[76:77], v[6:7]
	v_pk_mul_f32 v[78:79], v[78:79], v[6:7]
	v_pk_mul_f32 v[80:81], v[80:81], v[6:7]
	v_cvt_pk_bf16_f32 v74, v74, v75
	v_cvt_pk_bf16_f32 v75, v76, v77
	v_cvt_pk_bf16_f32 v76, v78, v79
	v_cvt_pk_bf16_f32 v77, v80, v81
	s_nop 1
	v_permlane32_swap_b32_e32 v74, v76
	v_permlane32_swap_b32_e32 v75, v77
	global_store_dwordx4 v[8:9], v[74:77], off offset:32
	v_pk_mul_f32 v[50:51], v[50:51], v[6:7]
	v_pk_mul_f32 v[52:53], v[52:53], v[6:7]
	v_pk_mul_f32 v[54:55], v[54:55], v[6:7]
	v_pk_mul_f32 v[56:57], v[56:57], v[6:7]
	v_cvt_pk_bf16_f32 v50, v50, v51
	v_cvt_pk_bf16_f32 v51, v52, v53
	v_cvt_pk_bf16_f32 v52, v54, v55
	v_cvt_pk_bf16_f32 v53, v56, v57
	s_nop 1
	v_permlane32_swap_b32_e32 v50, v52
	v_permlane32_swap_b32_e32 v51, v53
	global_store_dwordx4 v[8:9], v[50:53], off offset:64
	v_pk_mul_f32 v[58:59], v[58:59], v[6:7]
	v_pk_mul_f32 v[60:61], v[60:61], v[6:7]
	v_pk_mul_f32 v[62:63], v[62:63], v[6:7]
	v_pk_mul_f32 v[64:65], v[64:65], v[6:7]
	v_cvt_pk_bf16_f32 v58, v58, v59
	v_cvt_pk_bf16_f32 v59, v60, v61
	v_cvt_pk_bf16_f32 v60, v62, v63
	v_cvt_pk_bf16_f32 v61, v64, v65
	s_nop 1
	v_permlane32_swap_b32_e32 v58, v60
	v_permlane32_swap_b32_e32 v59, v61
	global_store_dwordx4 v[8:9], v[58:61], off offset:96
	v_pk_mul_f32 v[34:35], v[34:35], v[6:7]
	v_pk_mul_f32 v[36:37], v[36:37], v[6:7]
	v_pk_mul_f32 v[38:39], v[38:39], v[6:7]
	v_pk_mul_f32 v[40:41], v[40:41], v[6:7]
	v_cvt_pk_bf16_f32 v34, v34, v35
	v_cvt_pk_bf16_f32 v35, v36, v37
	v_cvt_pk_bf16_f32 v36, v38, v39
	v_cvt_pk_bf16_f32 v37, v40, v41
	s_nop 1
	v_permlane32_swap_b32_e32 v34, v36
	v_permlane32_swap_b32_e32 v35, v37
	global_store_dwordx4 v[8:9], v[34:37], off offset:128
	v_pk_mul_f32 v[42:43], v[42:43], v[6:7]
	v_pk_mul_f32 v[44:45], v[44:45], v[6:7]
	v_pk_mul_f32 v[46:47], v[46:47], v[6:7]
	v_pk_mul_f32 v[48:49], v[48:49], v[6:7]
	v_cvt_pk_bf16_f32 v42, v42, v43
	v_cvt_pk_bf16_f32 v43, v44, v45
	v_cvt_pk_bf16_f32 v44, v46, v47
	v_cvt_pk_bf16_f32 v45, v48, v49
	s_nop 1
	v_permlane32_swap_b32_e32 v42, v44
	v_permlane32_swap_b32_e32 v43, v45
	global_store_dwordx4 v[8:9], v[42:45], off offset:160
	v_pk_mul_f32 v[18:19], v[18:19], v[6:7]
	v_pk_mul_f32 v[20:21], v[20:21], v[6:7]
	v_pk_mul_f32 v[22:23], v[22:23], v[6:7]
	v_pk_mul_f32 v[24:25], v[24:25], v[6:7]
	v_cvt_pk_bf16_f32 v18, v18, v19
	v_cvt_pk_bf16_f32 v19, v20, v21
	v_cvt_pk_bf16_f32 v20, v22, v23
	v_cvt_pk_bf16_f32 v21, v24, v25
	s_nop 1
	v_permlane32_swap_b32_e32 v18, v20
	v_permlane32_swap_b32_e32 v19, v21
	global_store_dwordx4 v[8:9], v[18:21], off offset:192
	v_pk_mul_f32 v[26:27], v[26:27], v[6:7]
	v_pk_mul_f32 v[28:29], v[28:29], v[6:7]
	v_pk_mul_f32 v[30:31], v[30:31], v[6:7]
	v_pk_mul_f32 v[32:33], v[32:33], v[6:7]
	v_cvt_pk_bf16_f32 v26, v26, v27
	v_cvt_pk_bf16_f32 v27, v28, v29
	v_cvt_pk_bf16_f32 v28, v30, v31
	v_cvt_pk_bf16_f32 v29, v32, v33
	s_nop 1
	v_permlane32_swap_b32_e32 v26, v28
	v_permlane32_swap_b32_e32 v27, v29
	global_store_dwordx4 v[8:9], v[26:29], off offset:224
	s_branch .LBB0_1316
.Lmemw1_slow:
	v_add_u32_e32 v2, s22, v178
	v_add_u32_e32 v4, s6, v2
	v_ashrrev_i32_e32 v4, 5, v4
	v_ashrrev_i32_e32 v5, 31, v4
	v_pk_mul_f32 v[8:9], v[66:67], v[6:7] op_sel_hi:[1,0]
	v_lshlrev_b64 v[4:5], 12, v[4:5]
	v_cvt_pk_bf16_f32 v10, v8, v9
	v_pk_mul_f32 v[8:9], v[68:69], v[6:7] op_sel_hi:[1,0]
	v_and_b32_e32 v2, 31, v2
	v_cvt_pk_bf16_f32 v11, v8, v9
	s_and_b64 vcc, exec, s[20:21]
	v_lshl_or_b32 v12, s7, 2, v4
	s_cbranch_vccz .LBB0_1254
	v_or_b32_e32 v8, v12, v2
	v_mov_b32_e32 v9, v5
	v_lshl_add_u64 v[8:9], v[8:9], 4, v[150:151]
	global_store_dwordx2 v[8:9], v[10:11], off
	s_mov_b64 s[18:19], 0
